# v57: v53 + P4 sample GLA spans: head-norm load no longer waited alone (LDS write deferred past the chunk-operand waits; one round trip less per span)
# speedup vs baseline: 1.0015x; 1.0015x over previous
; #define LAS __attribute__((address_space(3)))
; template <bool FULL, bool PARTIAL  > ...
;     ...
;     float wal[8];
; #pragma unroll
;     for (int i = 0; i < 8; ++i) wal[i] = w_alpha[(2 * i + h) * 512 + hd * 128 + kk];
;     const float bal = b_alpha[hd * 128 + kk];
;     f32x16 Sacc[4];
;     float dsum = 0.f;
;     if (FULL && tid < 256) ((LAS float*)(lds + OFF_HN))[tid] = head_norm[tid];
.LBB0_1072:
	v_readfirstlane_b32 s30, v0
	s_lshr_b32 s31, s30, 6
	s_lshl_b32 s26, s31, 5
	s_and_b32 s45, s10, 3
	s_and_b32 s34, s26, 0x60
	v_or_b32_e32 v83, s34, v165
	s_lshl_b32 s42, s45, 7
	v_or3_b32 v2, s42, v149, v83
	v_lshlrev_b32_e32 v114, 2, v2
	v_lshl_add_u64 v[2:3], s[56:57], 0, v[114:115]
	s_movk_i32 s34, 0x2000
	v_add_co_u32_e32 v4, vcc, s34, v2
	s_movk_i32 s34, 0x4000
	s_nop 0
	v_addc_co_u32_e32 v5, vcc, 0, v3, vcc
	global_load_dword v84, v114, s[56:57]
	global_load_dword v86, v[4:5], off offset:-4096
	global_load_dword v85, v[4:5], off
	v_add_co_u32_e32 v4, vcc, s34, v2
	s_movk_i32 s34, 0x5000
	s_nop 0
	v_addc_co_u32_e32 v5, vcc, 0, v3, vcc
	global_load_dword v88, v[4:5], off offset:-4096
	global_load_dword v87, v[4:5], off
	v_add_co_u32_e32 v4, vcc, s34, v2
	s_nop 1
	v_addc_co_u32_e32 v5, vcc, 0, v3, vcc
	global_load_dword v89, v[4:5], off
	v_add_co_u32_e32 v4, vcc, 0x6000, v2
	s_nop 1
	v_addc_co_u32_e32 v5, vcc, 0, v3, vcc
	v_add_co_u32_e32 v2, vcc, 0x7000, v2
	global_load_dword v90, v[4:5], off
	s_nop 0
	v_addc_co_u32_e32 v3, vcc, 0, v3, vcc
	global_load_dword v82, v[2:3], off
	v_or_b32_e32 v2, s42, v83
	v_lshlrev_b32_e32 v2, 2, v2
	global_load_dword v2, v2, s[58:59]
	s_and_saveexec_b64 s[34:35], s[0:1]
	s_cbranch_execz .LBB0_1074
	global_load_dword v255, v[116:117], off
; template <bool FULL, bool PARTIAL  > ...
;     ...
;     const int nv1 = nvalid - 1;
;     const u32x4 z4 = (u32x4){0u, 0u, 0u, 0u};
;     ...
;     GLA_FETCH_KG(0);
;     asm volatile("" :: "v"(raw_ga), "v"(raw_k[0]), "v"(raw_k[1]));
;     if (FULL) asm volatile("" :: "v"(raw_q[0]), "v"(raw_q[1]));
;     if (FULL && S0) {
;         const float* s0p = S0 + (size_t)(4 * h) * 256 + 32 * w + r;
; #pragma unroll
;         for (int kb = 0; kb < 4; ++kb)
; #pragma unroll
;             for (int i = 0; i < 16; ++i) Sacc[kb][i] = s0p[(32 * kb + (i & 3) + 8 * (i >> 2)) * 256];
.LBB0_1074:
	s_or_b64 exec, exec, s[34:35]
	s_and_b32 s34, s11, -16
	s_addk_i32 s34, 0x4000
	s_ashr_i32 s35, s34, 31
	v_mov_b32_e32 v3, v0
	s_lshl_b64 s[38:39], s[34:35], 6
	s_add_u32 s52, s96, s38
	v_ashrrev_i32_e32 v24, 2, v3
	v_lshlrev_b32_e32 v5, 2, v3
	s_addc_u32 s53, s97, s39
	s_lshl_b64 s[38:39], s[34:35], 11
	v_min_i32_e32 v4, 15, v24
	v_and_b32_e32 v5, 12, v5
	s_add_u32 s43, s40, s38
	v_lshl_or_b32 v114, v4, 4, v5
	s_addc_u32 s54, s41, s39
	s_lshl_b32 s42, s42, 1
	v_lshl_add_u64 v[4:5], v[114:115], 2, s[52:53]
	v_ashrrev_i32_e32 v18, 4, v3
	v_lshlrev_b32_e32 v3, 3, v3
	s_add_u32 s42, s43, s42
	global_load_dwordx4 v[20:23], v[4:5], off
	v_and_b32_e32 v3, 0x78, v3
	v_min_i32_e32 v4, 15, v18
	s_addc_u32 s43, s54, 0
	v_lshl_or_b32 v114, v4, 10, v3
	v_lshl_add_u64 v[8:9], v[114:115], 1, s[42:43]
	global_load_dwordx4 v[4:7], v[8:9], off offset:1024
	v_min_i32_e32 v12, 0xffffffef, v18
	global_load_dwordx4 v[8:11], v[8:9], off
	v_lshl_or_b32 v3, v12, 10, v3
	v_add_u32_e32 v114, 0x8000, v3
	v_cmp_gt_i32_e32 vcc, 16, v18
	v_lshl_add_u64 v[16:17], v[114:115], 1, s[42:43]
	global_load_dwordx4 v[12:15], v[16:17], off offset:1024
	s_waitcnt vmcnt(2)
	v_cndmask_b32_e32 v7, 0, v7, vcc
	v_cndmask_b32_e32 v6, 0, v6, vcc
	v_cndmask_b32_e32 v5, 0, v5, vcc
	v_cndmask_b32_e32 v4, 0, v4, vcc
	s_waitcnt vmcnt(1)
	v_cndmask_b32_e32 v11, 0, v11, vcc
	v_cndmask_b32_e32 v10, 0, v10, vcc
	v_cndmask_b32_e32 v9, 0, v9, vcc
	v_cndmask_b32_e32 v8, 0, v8, vcc
	v_cmp_gt_i32_e32 vcc, -16, v18
	global_load_dwordx4 v[16:19], v[16:17], off
	s_waitcnt vmcnt(1)
	v_cndmask_b32_e32 v15, 0, v15, vcc
	v_cndmask_b32_e32 v14, 0, v14, vcc
	v_cndmask_b32_e32 v13, 0, v13, vcc
	v_cndmask_b32_e32 v12, 0, v12, vcc
	s_waitcnt vmcnt(0)
	s_and_saveexec_b64 s[100:101], s[0:1]
	ds_write_b32 v150, v255
	s_mov_b64 exec, s[100:101]
	v_cndmask_b32_e32 v19, 0, v19, vcc
	v_cndmask_b32_e32 v18, 0, v18, vcc
	v_cndmask_b32_e32 v17, 0, v17, vcc
	v_cndmask_b32_e32 v16, 0, v16, vcc
	v_cmp_gt_i32_e32 vcc, 16, v24
	s_nop 1
	v_cndmask_b32_e32 v23, 0, v23, vcc
	v_cndmask_b32_e32 v22, 0, v22, vcc
	v_cndmask_b32_e32 v21, 0, v21, vcc
	v_cndmask_b32_e32 v20, 0, v20, vcc
	s_and_b64 vcc, exec, s[28:29]
	s_cbranch_vccz .LBB0_1091
	s_lshl_b64 s[42:43], s[30:31], 1
	s_and_b32 s43, s43, 1
	s_and_b32 s42, s42, 0xffffff80
	v_lshl_add_u64 v[24:25], v[120:121], 0, v[118:119]
	v_lshl_add_u64 v[24:25], v[24:25], 0, s[42:43]
	v_add_co_u32_e32 v26, vcc, 0x2000, v24
	s_nop 1
	v_addc_co_u32_e32 v27, vcc, 0, v25, vcc
	global_load_dword v40, v[24:25], off
	global_load_dword v41, v[24:25], off offset:1024
	global_load_dword v44, v[24:25], off offset:2048
	global_load_dword v45, v[24:25], off offset:3072
	global_load_dword v46, v[26:27], off
	global_load_dword v47, v[26:27], off offset:1024
	global_load_dword v48, v[26:27], off offset:2048
	global_load_dword v49, v[26:27], off offset:3072
	v_add_co_u32_e32 v26, vcc, 0x4000, v24
	s_nop 1
	v_addc_co_u32_e32 v27, vcc, 0, v25, vcc
	v_add_co_u32_e32 v28, vcc, 0x6000, v24
	s_nop 1
	v_addc_co_u32_e32 v29, vcc, 0, v25, vcc
	global_load_dword v132, v[26:27], off
	global_load_dword v133, v[26:27], off offset:1024
	global_load_dword v134, v[26:27], off offset:2048
	global_load_dword v135, v[26:27], off offset:3072
	global_load_dword v136, v[28:29], off
	global_load_dword v137, v[28:29], off offset:1024
	global_load_dword v138, v[28:29], off offset:2048
	global_load_dword v139, v[28:29], off offset:3072
	v_add_co_u32_e32 v26, vcc, 0x8000, v24
	s_nop 1
	v_addc_co_u32_e32 v27, vcc, 0, v25, vcc
	v_add_co_u32_e32 v28, vcc, 0xa000, v24
	s_nop 1
	v_addc_co_u32_e32 v29, vcc, 0, v25, vcc
	global_load_dword v34, v[26:27], off
	global_load_dword v35, v[26:27], off offset:1024
	global_load_dword v36, v[26:27], off offset:2048
	global_load_dword v37, v[26:27], off offset:3072
	global_load_dword v38, v[28:29], off
	global_load_dword v39, v[28:29], off offset:1024
	global_load_dword v42, v[28:29], off offset:2048
	global_load_dword v43, v[28:29], off offset:3072
	v_add_co_u32_e32 v26, vcc, 0xc000, v24
	s_nop 1
	v_addc_co_u32_e32 v27, vcc, 0, v25, vcc
	v_add_co_u32_e32 v28, vcc, 0xe000, v24
	s_nop 1
	v_addc_co_u32_e32 v29, vcc, 0, v25, vcc
	global_load_dword v124, v[26:27], off
	global_load_dword v125, v[26:27], off offset:1024
	global_load_dword v126, v[26:27], off offset:2048
	global_load_dword v127, v[26:27], off offset:3072
	global_load_dword v128, v[28:29], off
	global_load_dword v129, v[28:29], off offset:1024
	global_load_dword v130, v[28:29], off offset:2048
	global_load_dword v131, v[28:29], off offset:3072
	v_add_co_u32_e32 v26, vcc, 0x10000, v24
	s_nop 1
	v_addc_co_u32_e32 v27, vcc, 0, v25, vcc
	v_add_co_u32_e32 v28, vcc, 0x12000, v24
	s_nop 1
	v_addc_co_u32_e32 v29, vcc, 0, v25, vcc
	global_load_dword v50, v[26:27], off
	global_load_dword v51, v[26:27], off offset:1024
	global_load_dword v52, v[26:27], off offset:2048
	global_load_dword v53, v[26:27], off offset:3072
	global_load_dword v54, v[28:29], off
	global_load_dword v55, v[28:29], off offset:1024
	global_load_dword v56, v[28:29], off offset:2048
	global_load_dword v57, v[28:29], off offset:3072
	v_add_co_u32_e32 v26, vcc, 0x14000, v24
	s_nop 1
	v_addc_co_u32_e32 v27, vcc, 0, v25, vcc
	v_add_co_u32_e32 v28, vcc, 0x16000, v24
	s_nop 1
	v_addc_co_u32_e32 v29, vcc, 0, v25, vcc
	global_load_dword v58, v[26:27], off
	global_load_dword v59, v[26:27], off offset:1024
	global_load_dword v60, v[26:27], off offset:2048
	global_load_dword v61, v[26:27], off offset:3072
	global_load_dword v62, v[28:29], off
	global_load_dword v63, v[28:29], off offset:1024
	global_load_dword v64, v[28:29], off offset:2048
	global_load_dword v65, v[28:29], off offset:3072
	v_add_co_u32_e32 v26, vcc, 0x18000, v24
	s_nop 1
	v_addc_co_u32_e32 v27, vcc, 0, v25, vcc
	v_add_co_u32_e32 v28, vcc, 0x1a000, v24
	s_nop 1
	v_addc_co_u32_e32 v29, vcc, 0, v25, vcc
	global_load_dword v66, v[26:27], off
	global_load_dword v67, v[26:27], off offset:1024
	global_load_dword v68, v[26:27], off offset:2048
	global_load_dword v69, v[26:27], off offset:3072
	global_load_dword v70, v[28:29], off
	global_load_dword v71, v[28:29], off offset:1024
	global_load_dword v72, v[28:29], off offset:2048
	global_load_dword v73, v[28:29], off offset:3072
	v_add_co_u32_e32 v26, vcc, 0x1c000, v24
	s_nop 1
	v_addc_co_u32_e32 v27, vcc, 0, v25, vcc
	v_add_co_u32_e32 v24, vcc, 0x1e000, v24
	s_nop 1
	v_addc_co_u32_e32 v25, vcc, 0, v25, vcc
	global_load_dword v74, v[26:27], off
	global_load_dword v75, v[26:27], off offset:1024
	global_load_dword v76, v[26:27], off offset:2048
	global_load_dword v77, v[26:27], off offset:3072
	global_load_dword v78, v[24:25], off
	global_load_dword v79, v[24:25], off offset:1024
	global_load_dword v80, v[24:25], off offset:2048
	global_load_dword v81, v[24:25], off offset:3072
	s_cbranch_execnz .LBB0_1077
